# phase D1: the four iterations' loads issued up front into four register banks, counted vmcnt waits (generic loop kept as fallback)
# speedup vs baseline: 1.0062x; 1.0011x over previous
; DI void phaseD1(int wv0, PP p, unsigned char* smem) {
;   const int tid = my_tid(wv0);
;   float* sB = (float*)smem;
;   {
;     const float* cbp = (const float*)(p->ws + OFF_CBP);
;     float bb = 0.f;
;     for (int sl = 0; sl < 32; ++sl) bb += cbp[((tid >> 8) * 32 + sl) * 256 + (tid & 255)];
;     sB[tid] = bb;
;   }
;   __syncthreads();
;   const float* PART = (const float*)(p->ws + OFF_CPART);
;   u16* HC = (u16*)(p->ws + OFF_HC);
;   for (int e = blockIdx.x * NT_ + tid; e < 2 * 4096 * 64; e += gridDim.x * NT_) {
.LBB0_521:
	s_load_dwordx2 s[2:3], s[2:3], 0xc8
	v_and_b32_e32 v0, 0xff, v2
	v_lshlrev_b32_e32 v1, 5, v2
	s_movk_i32 s0, 0xe000
	v_and_or_b32 v0, v1, s0, v0
	v_ashrrev_i32_e32 v1, 31, v0
	s_waitcnt lgkmcnt(0)
	v_lshl_add_u64 v[0:1], v[0:1], 2, s[2:3]
	v_add_co_u32_e32 v6, vcc, 0x1fc0000, v0
	s_mov_b64 s[0:1], 0x1fc0000
	s_nop 0
	v_addc_co_u32_e32 v7, vcc, 0, v1, vcc
	v_add_co_u32_e32 v8, vcc, 0x1fc1000, v0
	v_lshl_add_u64 v[4:5], v[0:1], 0, s[0:1]
	s_nop 0
	v_addc_co_u32_e32 v9, vcc, 0, v1, vcc
	global_load_dword v3, v[6:7], off
	global_load_dword v10, v[4:5], off offset:1024
	global_load_dword v11, v[4:5], off offset:2048
	global_load_dword v12, v[8:9], off
	global_load_dword v13, v[8:9], off offset:1024
	global_load_dword v14, v[8:9], off offset:2048
	global_load_dword v15, v[8:9], off offset:3072
	global_load_dword v16, v[4:5], off offset:3072
	v_add_co_u32_e32 v4, vcc, 0x1fc2000, v0
	s_mov_b32 s0, 0x80000
	s_nop 0
	v_addc_co_u32_e32 v5, vcc, 0, v1, vcc
	v_add_co_u32_e32 v6, vcc, 0x1fc3000, v0
	s_waitcnt vmcnt(0)
	v_add_f32_e32 v3, 0, v3
	v_addc_co_u32_e32 v7, vcc, 0, v1, vcc
	global_load_dword v8, v[4:5], off
	global_load_dword v9, v[4:5], off offset:1024
	global_load_dword v17, v[4:5], off offset:2048
	global_load_dword v18, v[4:5], off offset:3072
	global_load_dword v19, v[6:7], off
	global_load_dword v20, v[6:7], off offset:1024
	global_load_dword v21, v[6:7], off offset:2048
	global_load_dword v22, v[6:7], off offset:3072
	v_add_co_u32_e32 v4, vcc, 0x1fc4000, v0
	v_add_f32_e32 v3, v3, v10
	s_nop 0
	v_addc_co_u32_e32 v5, vcc, 0, v1, vcc
	v_add_co_u32_e32 v6, vcc, 0x1fc5000, v0
	v_add_f32_e32 v3, v3, v11
	s_nop 0
	v_addc_co_u32_e32 v7, vcc, 0, v1, vcc
	global_load_dword v23, v[4:5], off
	global_load_dword v24, v[4:5], off offset:1024
	global_load_dword v25, v[4:5], off offset:2048
	global_load_dword v26, v[4:5], off offset:3072
	global_load_dword v27, v[6:7], off
	global_load_dword v28, v[6:7], off offset:1024
	global_load_dword v29, v[6:7], off offset:2048
	global_load_dword v30, v[6:7], off offset:3072
	v_add_co_u32_e32 v4, vcc, 0x1fc6000, v0
	v_add_f32_e32 v3, v3, v16
	s_nop 0
	v_addc_co_u32_e32 v5, vcc, 0, v1, vcc
	v_add_co_u32_e32 v0, vcc, 0x1fc7000, v0
	v_add_f32_e32 v3, v3, v12
	s_nop 0
	v_addc_co_u32_e32 v1, vcc, 0, v1, vcc
	global_load_dword v6, v[4:5], off
	global_load_dword v7, v[4:5], off offset:1024
	global_load_dword v31, v[4:5], off offset:2048
	global_load_dword v32, v[4:5], off offset:3072
	global_load_dword v33, v[0:1], off
	global_load_dword v34, v[0:1], off offset:1024
	global_load_dword v35, v[0:1], off offset:2048
	global_load_dword v36, v[0:1], off offset:3072
	v_add_f32_e32 v3, v3, v13
	v_add_f32_e32 v3, v3, v14
	v_add_f32_e32 v3, v3, v15
	v_lshl_add_u32 v0, s94, 9, v2
	v_lshl_add_u32 v1, v2, 2, 32
	v_cmp_gt_i32_e32 vcc, s0, v0
	s_waitcnt vmcnt(23)
	v_add_f32_e32 v3, v3, v8
	s_waitcnt vmcnt(22)
	v_add_f32_e32 v3, v3, v9
	s_waitcnt vmcnt(21)
	v_add_f32_e32 v3, v3, v17
	s_waitcnt vmcnt(20)
	v_add_f32_e32 v3, v3, v18
	s_waitcnt vmcnt(19)
	v_add_f32_e32 v3, v3, v19
	s_waitcnt vmcnt(18)
	v_add_f32_e32 v3, v3, v20
	s_waitcnt vmcnt(17)
	v_add_f32_e32 v3, v3, v21
	s_waitcnt vmcnt(16)
	v_add_f32_e32 v3, v3, v22
	s_waitcnt vmcnt(15)
	v_add_f32_e32 v3, v3, v23
	s_waitcnt vmcnt(14)
	v_add_f32_e32 v3, v3, v24
	s_waitcnt vmcnt(13)
	v_add_f32_e32 v3, v3, v25
	s_waitcnt vmcnt(12)
	v_add_f32_e32 v3, v3, v26
	s_waitcnt vmcnt(11)
	v_add_f32_e32 v3, v3, v27
	s_waitcnt vmcnt(10)
	v_add_f32_e32 v3, v3, v28
	s_waitcnt vmcnt(9)
	v_add_f32_e32 v3, v3, v29
	s_waitcnt vmcnt(8)
	v_add_f32_e32 v3, v3, v30
	s_waitcnt vmcnt(7)
	v_add_f32_e32 v3, v3, v6
	s_waitcnt vmcnt(6)
	v_add_f32_e32 v3, v3, v7
	s_waitcnt vmcnt(5)
	v_add_f32_e32 v3, v3, v31
	s_waitcnt vmcnt(4)
	v_add_f32_e32 v3, v3, v32
	s_waitcnt vmcnt(3)
	v_add_f32_e32 v3, v3, v33
	s_waitcnt vmcnt(2)
	v_add_f32_e32 v3, v3, v34
	s_waitcnt vmcnt(1)
	v_add_f32_e32 v3, v3, v35
	s_waitcnt vmcnt(0)
	v_add_f32_e32 v3, v3, v36
	ds_write_b32 v1, v3
	s_waitcnt lgkmcnt(0)
	s_barrier
	s_and_saveexec_b64 s[8:9], vcc
	s_cbranch_execz .LBB0_524
	s_load_dword s1, s[90:91], 0xd8
	s_add_u32 s12, s2, 0x1c3d4100
	s_addc_u32 s13, s3, 0
	s_add_u32 s14, s2, 0x26d4100
	v_lshlrev_b32_e32 v1, 2, v2
	s_addc_u32 s15, s3, 0
	s_waitcnt lgkmcnt(0)
	s_lshl_b32 s0, s1, 9
	v_lshl_add_u32 v1, s94, 11, v1
	s_lshl_b32 s1, s1, 11
	s_mov_b64 s[16:17], 0
	s_mov_b32 s18, 0xffffc
	s_mov_b32 s19, 0x800000
	s_mov_b32 s20, 0x1000000
	s_mov_b32 s21, 0x1800000
	s_mov_b32 s22, 0x7ffff
	s_cmp_eq_u32 s0, 0x20000
	s_cbranch_scc0 .LBB0_523
; DI uint2 pk4(float a, float b, float c, float d) { uint2 o; o.x = pk2(a, b); o.y = pk2(c, d); return o; }
; DI void phaseD1(int wv0, PP p, unsigned char* smem) {
;     ...
;   for (int e = blockIdx.x * NT_ + tid; e < 2 * 4096 * 64; e += gridDim.x * NT_) {
;     const int kv = e >> 18, rc = e & 262143, c4 = (rc & 63) * 4;
;     const size_t o = (size_t)kv * 4096 * 256 + (size_t)rc * 4;
;     float4 a = *(const float4*)(PART + o);
; #pragma unroll
;     for (int ks = 1; ks < 4; ++ks) {
;       const float4 t = *(const float4*)(PART + (size_t)ks * 2 * 4096 * 256 + o);
;       a.x += t.x; a.y += t.y; a.z += t.z; a.w += t.w;
;     }
;     const float* bv = sB + kv * 256 + c4;
;     *(uint2*)(HC + o) = pk4(gelu_t(a.x + bv[0]), gelu_t(a.y + bv[1]), gelu_t(a.z + bv[2]), gelu_t(a.w + bv[3]));
;   }
	v_ashrrev_i32_e32 v42, 18, v0
	v_ashrrev_i32_e32 v43, 31, v42
	v_lshlrev_b64 v[62:63], 20, v[42:43]
	v_and_or_b32 v62, v1, s18, v62
	v_lshl_add_u64 v[54:55], v[62:63], 2, s[12:13]
	v_add_co_u32_e32 v56, vcc, s19, v54
	v_and_b32_e32 v44, 0xfc, v1
	s_nop 0
	v_addc_co_u32_e32 v57, vcc, 0, v55, vcc
	v_add_co_u32_e32 v58, vcc, s20, v54
	v_lshlrev_b32_e32 v60, 10, v42
	s_nop 0
	v_addc_co_u32_e32 v59, vcc, 0, v55, vcc
	v_lshlrev_b32_e32 v61, 2, v44
	global_load_dwordx4 v[42:45], v[54:55], off
	v_add_co_u32_e32 v54, vcc, s21, v54
	global_load_dwordx4 v[46:49], v[56:57], off
	global_load_dwordx4 v[50:53], v[58:59], off
	v_addc_co_u32_e32 v55, vcc, 0, v55, vcc
	global_load_dwordx4 v[54:57], v[54:55], off
	v_add3_u32 v58, 32, v60, v61
	ds_read_b128 v[58:61], v58
	v_add_u32_e32 v0, s0, v0
	v_add_u32_e32 v1, s1, v1
	v_lshl_add_u64 v[62:63], v[62:63], 1, s[14:15]
	v_ashrrev_i32_e32 v74, 18, v0
	v_ashrrev_i32_e32 v75, 31, v74
	v_lshlrev_b64 v[94:95], 20, v[74:75]
	v_and_or_b32 v94, v1, s18, v94
	v_lshl_add_u64 v[86:87], v[94:95], 2, s[12:13]
	v_add_co_u32_e32 v88, vcc, s19, v86
	v_and_b32_e32 v76, 0xfc, v1
	s_nop 0
	v_addc_co_u32_e32 v89, vcc, 0, v87, vcc
	v_add_co_u32_e32 v90, vcc, s20, v86
	v_lshlrev_b32_e32 v92, 10, v74
	s_nop 0
	v_addc_co_u32_e32 v91, vcc, 0, v87, vcc
	v_lshlrev_b32_e32 v93, 2, v76
	global_load_dwordx4 v[74:77], v[86:87], off
	v_add_co_u32_e32 v86, vcc, s21, v86
	global_load_dwordx4 v[78:81], v[88:89], off
	global_load_dwordx4 v[82:85], v[90:91], off
	v_addc_co_u32_e32 v87, vcc, 0, v87, vcc
	global_load_dwordx4 v[86:89], v[86:87], off
	v_add3_u32 v90, 32, v92, v93
	ds_read_b128 v[90:93], v90
	v_add_u32_e32 v0, s0, v0
	v_add_u32_e32 v1, s1, v1
	v_lshl_add_u64 v[94:95], v[94:95], 1, s[14:15]
	v_ashrrev_i32_e32 v106, 18, v0
	v_ashrrev_i32_e32 v107, 31, v106
	v_lshlrev_b64 v[126:127], 20, v[106:107]
	v_and_or_b32 v126, v1, s18, v126
	v_lshl_add_u64 v[118:119], v[126:127], 2, s[12:13]
	v_add_co_u32_e32 v120, vcc, s19, v118
	v_and_b32_e32 v108, 0xfc, v1
	s_nop 0
	v_addc_co_u32_e32 v121, vcc, 0, v119, vcc
	v_add_co_u32_e32 v122, vcc, s20, v118
	v_lshlrev_b32_e32 v124, 10, v106
	s_nop 0
	v_addc_co_u32_e32 v123, vcc, 0, v119, vcc
	v_lshlrev_b32_e32 v125, 2, v108
	global_load_dwordx4 v[106:109], v[118:119], off
	v_add_co_u32_e32 v118, vcc, s21, v118
	global_load_dwordx4 v[110:113], v[120:121], off
	global_load_dwordx4 v[114:117], v[122:123], off
	v_addc_co_u32_e32 v119, vcc, 0, v119, vcc
	global_load_dwordx4 v[118:121], v[118:119], off
	v_add3_u32 v122, 32, v124, v125
	ds_read_b128 v[122:125], v122
	v_add_u32_e32 v0, s0, v0
	v_add_u32_e32 v1, s1, v1
	v_lshl_add_u64 v[126:127], v[126:127], 1, s[14:15]
	v_ashrrev_i32_e32 v152, 18, v0
	v_ashrrev_i32_e32 v153, 31, v152
	v_lshlrev_b64 v[172:173], 20, v[152:153]
	v_and_or_b32 v172, v1, s18, v172
	v_lshl_add_u64 v[164:165], v[172:173], 2, s[12:13]
	v_add_co_u32_e32 v166, vcc, s19, v164
	v_and_b32_e32 v154, 0xfc, v1
	s_nop 0
	v_addc_co_u32_e32 v167, vcc, 0, v165, vcc
	v_add_co_u32_e32 v168, vcc, s20, v164
	v_lshlrev_b32_e32 v170, 10, v152
	s_nop 0
	v_addc_co_u32_e32 v169, vcc, 0, v165, vcc
	v_lshlrev_b32_e32 v171, 2, v154
	global_load_dwordx4 v[152:155], v[164:165], off
	v_add_co_u32_e32 v164, vcc, s21, v164
	global_load_dwordx4 v[156:159], v[166:167], off
	global_load_dwordx4 v[160:163], v[168:169], off
	v_addc_co_u32_e32 v165, vcc, 0, v165, vcc
	global_load_dwordx4 v[164:167], v[164:165], off
	v_add3_u32 v168, 32, v170, v171
	ds_read_b128 v[168:171], v168
	v_add_u32_e32 v0, s0, v0
	v_add_u32_e32 v1, s1, v1
	v_lshl_add_u64 v[172:173], v[172:173], 1, s[14:15]
	s_waitcnt vmcnt(14)
	v_pk_add_f32 v[42:43], v[42:43], v[46:47]
	s_waitcnt vmcnt(13)
	v_pk_add_f32 v[42:43], v[42:43], v[50:51]
	v_pk_add_f32 v[44:45], v[44:45], v[48:49]
	s_waitcnt vmcnt(12)
	v_pk_add_f32 v[42:43], v[42:43], v[54:55]
	v_pk_add_f32 v[44:45], v[44:45], v[52:53]
	s_waitcnt lgkmcnt(0)
	v_pk_add_f32 v[42:43], v[42:43], v[58:59]
	v_pk_add_f32 v[44:45], v[44:45], v[56:57]
	v_mul_f32_e32 v50, 0x3d372713, v42
	v_mul_f32_e32 v51, 0x3d372713, v43
	v_pk_add_f32 v[44:45], v[44:45], v[60:61]
	v_mul_f32_e32 v50, v42, v50
	v_mul_f32_e32 v51, v43, v51
	v_pk_mul_f32 v[46:47], v[42:43], 0.5 op_sel_hi:[1,0]
	v_mul_f32_e32 v52, 0x3d372713, v44
	v_mul_f32_e32 v53, 0x3d372713, v45
	v_fma_f32 v42, v42, v50, v42
	v_fma_f32 v43, v43, v51, v43
	v_mul_f32_e32 v52, v44, v52
	v_mul_f32_e32 v53, v45, v53
	v_mul_f32_e32 v42, 0x3f4c422a, v42
	v_mul_f32_e32 v43, 0x3f4c422a, v43
	v_pk_mul_f32 v[48:49], v[44:45], 0.5 op_sel_hi:[1,0]
	v_fma_f32 v44, v44, v52, v44
	v_fma_f32 v45, v45, v53, v45
	v_add_f32_e32 v42, v42, v42
	v_add_f32_e32 v43, v43, v43
	v_mul_f32_e32 v44, 0x3f4c422a, v44
	v_mul_f32_e32 v45, 0x3f4c422a, v45
	v_mul_f32_e32 v42, 0x3fb8aa3b, v42
	v_mul_f32_e32 v43, 0x3fb8aa3b, v43
	v_add_f32_e32 v44, v44, v44
	v_add_f32_e32 v45, v45, v45
	v_exp_f32_e32 v42, v42
	v_exp_f32_e32 v43, v43
	v_mul_f32_e32 v44, 0x3fb8aa3b, v44
	v_mul_f32_e32 v45, 0x3fb8aa3b, v45
	v_exp_f32_e32 v44, v44
	v_exp_f32_e32 v45, v45
	v_pk_add_f32 v[42:43], v[42:43], 1.0 op_sel_hi:[1,0]
	v_pk_add_f32 v[44:45], v[44:45], 1.0 op_sel_hi:[1,0]
	v_div_scale_f32 v50, s[2:3], v43, v43, 2.0
	v_div_scale_f32 v52, s[2:3], v42, v42, 2.0
	v_rcp_f32_e32 v58, v50
	v_div_scale_f32 v54, s[4:5], v45, v45, 2.0
	v_rcp_f32_e32 v59, v52
	v_div_scale_f32 v56, s[6:7], v44, v44, 2.0
	v_rcp_f32_e32 v60, v54
	v_rcp_f32_e32 v61, v56
	v_fma_f32 v64, -v50, v58, 1.0
	v_div_scale_f32 v51, vcc, 2.0, v43, 2.0
	v_fma_f32 v65, -v52, v59, 1.0
	v_fmac_f32_e32 v58, v64, v58
	v_div_scale_f32 v53, s[2:3], 2.0, v42, 2.0
	v_fma_f32 v66, -v54, v60, 1.0
	v_fmac_f32_e32 v59, v65, v59
	v_mul_f32_e32 v64, v51, v58
; DI uint2 pk4(float a, float b, float c, float d) { uint2 o; o.x = pk2(a, b); o.y = pk2(c, d); return o; }
; DI void phaseD1(int wv0, PP p, unsigned char* smem) {
;     ...
;     const int kv = e >> 18, rc = e & 262143, c4 = (rc & 63) * 4;
;     const size_t o = (size_t)kv * 4096 * 256 + (size_t)rc * 4;
;     float4 a = *(const float4*)(PART + o);
; #pragma unroll
;     for (int ks = 1; ks < 4; ++ks) {
;       const float4 t = *(const float4*)(PART + (size_t)ks * 2 * 4096 * 256 + o);
;       a.x += t.x; a.y += t.y; a.z += t.z; a.w += t.w;
;     }
;     const float* bv = sB + kv * 256 + c4;
;     *(uint2*)(HC + o) = pk4(gelu_t(a.x + bv[0]), gelu_t(a.y + bv[1]), gelu_t(a.z + bv[2]), gelu_t(a.w + bv[3]));
	v_div_scale_f32 v55, s[4:5], 2.0, v45, 2.0
	v_fma_f32 v67, -v56, v61, 1.0
	v_fmac_f32_e32 v60, v66, v60
	v_mul_f32_e32 v65, v53, v59
	v_fma_f32 v68, -v50, v64, v51
	v_div_scale_f32 v57, s[6:7], 2.0, v44, 2.0
	v_fmac_f32_e32 v61, v67, v61
	v_mul_f32_e32 v66, v55, v60
	v_fma_f32 v69, -v52, v65, v53
	v_fmac_f32_e32 v64, v68, v58
	v_mul_f32_e32 v67, v57, v61
	v_fma_f32 v70, -v54, v66, v55
	v_fmac_f32_e32 v65, v69, v59
	v_fma_f32 v50, -v50, v64, v51
	v_fma_f32 v71, -v56, v67, v57
	v_fmac_f32_e32 v66, v70, v60
	v_fma_f32 v51, -v52, v65, v53
	v_div_fmas_f32 v50, v50, v58, v64
	s_mov_b64 vcc, s[2:3]
	v_fmac_f32_e32 v67, v71, v61
	v_fma_f32 v52, -v54, v66, v55
	v_div_fixup_f32 v43, v50, v43, 2.0
	v_div_fmas_f32 v50, v51, v59, v65
	s_mov_b64 vcc, s[4:5]
	v_fma_f32 v53, -v56, v67, v57
	v_div_fixup_f32 v42, v50, v42, 2.0
	v_div_fmas_f32 v50, v52, v60, v66
	s_mov_b64 vcc, s[6:7]
	v_div_fixup_f32 v45, v50, v45, 2.0
	v_div_fmas_f32 v50, v53, v61, v67
	v_div_fixup_f32 v44, v50, v44, 2.0
	v_pk_add_f32 v[42:43], v[42:43], 1.0 op_sel_hi:[1,0] neg_lo:[1,0] neg_hi:[1,0]
	v_pk_add_f32 v[44:45], v[44:45], 1.0 op_sel_hi:[1,0] neg_lo:[1,0] neg_hi:[1,0]
	v_pk_add_f32 v[42:43], v[42:43], 1.0 op_sel_hi:[1,0]
	v_pk_add_f32 v[44:45], v[44:45], 1.0 op_sel_hi:[1,0]
	v_pk_mul_f32 v[42:43], v[46:47], v[42:43]
	v_pk_mul_f32 v[44:45], v[48:49], v[44:45]
	v_cvt_pk_bf16_f32 v42, v42, v43
	v_cvt_pk_bf16_f32 v43, v44, v45
	global_store_dwordx2 v[62:63], v[42:43], off
	s_waitcnt vmcnt(11)
	v_pk_add_f32 v[74:75], v[74:75], v[78:79]
	s_waitcnt vmcnt(10)
	v_pk_add_f32 v[74:75], v[74:75], v[82:83]
	v_pk_add_f32 v[76:77], v[76:77], v[80:81]
	s_waitcnt vmcnt(9)
	v_pk_add_f32 v[74:75], v[74:75], v[86:87]
	v_pk_add_f32 v[76:77], v[76:77], v[84:85]
	s_waitcnt lgkmcnt(0)
	v_pk_add_f32 v[74:75], v[74:75], v[90:91]
	v_pk_add_f32 v[76:77], v[76:77], v[88:89]
	v_mul_f32_e32 v82, 0x3d372713, v74
	v_mul_f32_e32 v83, 0x3d372713, v75
	v_pk_add_f32 v[76:77], v[76:77], v[92:93]
	v_mul_f32_e32 v82, v74, v82
	v_mul_f32_e32 v83, v75, v83
	v_pk_mul_f32 v[78:79], v[74:75], 0.5 op_sel_hi:[1,0]
	v_mul_f32_e32 v84, 0x3d372713, v76
	v_mul_f32_e32 v85, 0x3d372713, v77
	v_fma_f32 v74, v74, v82, v74
	v_fma_f32 v75, v75, v83, v75
	v_mul_f32_e32 v84, v76, v84
	v_mul_f32_e32 v85, v77, v85
	v_mul_f32_e32 v74, 0x3f4c422a, v74
	v_mul_f32_e32 v75, 0x3f4c422a, v75
	v_pk_mul_f32 v[80:81], v[76:77], 0.5 op_sel_hi:[1,0]
	v_fma_f32 v76, v76, v84, v76
	v_fma_f32 v77, v77, v85, v77
	v_add_f32_e32 v74, v74, v74
	v_add_f32_e32 v75, v75, v75
	v_mul_f32_e32 v76, 0x3f4c422a, v76
	v_mul_f32_e32 v77, 0x3f4c422a, v77
	v_mul_f32_e32 v74, 0x3fb8aa3b, v74
	v_mul_f32_e32 v75, 0x3fb8aa3b, v75
	v_add_f32_e32 v76, v76, v76
	v_add_f32_e32 v77, v77, v77
	v_exp_f32_e32 v74, v74
	v_exp_f32_e32 v75, v75
	v_mul_f32_e32 v76, 0x3fb8aa3b, v76
	v_mul_f32_e32 v77, 0x3fb8aa3b, v77
	v_exp_f32_e32 v76, v76
	v_exp_f32_e32 v77, v77
	v_pk_add_f32 v[74:75], v[74:75], 1.0 op_sel_hi:[1,0]
	v_pk_add_f32 v[76:77], v[76:77], 1.0 op_sel_hi:[1,0]
	v_div_scale_f32 v82, s[2:3], v75, v75, 2.0
	v_div_scale_f32 v84, s[2:3], v74, v74, 2.0
	v_rcp_f32_e32 v90, v82
	v_div_scale_f32 v86, s[4:5], v77, v77, 2.0
	v_rcp_f32_e32 v91, v84
	v_div_scale_f32 v88, s[6:7], v76, v76, 2.0
	v_rcp_f32_e32 v92, v86
	v_rcp_f32_e32 v93, v88
	v_fma_f32 v96, -v82, v90, 1.0
	v_div_scale_f32 v83, vcc, 2.0, v75, 2.0
	v_fma_f32 v97, -v84, v91, 1.0
	v_fmac_f32_e32 v90, v96, v90
	v_div_scale_f32 v85, s[2:3], 2.0, v74, 2.0
	v_fma_f32 v98, -v86, v92, 1.0
	v_fmac_f32_e32 v91, v97, v91
	v_mul_f32_e32 v96, v83, v90
	v_div_scale_f32 v87, s[4:5], 2.0, v77, 2.0
	v_fma_f32 v99, -v88, v93, 1.0
	v_fmac_f32_e32 v92, v98, v92
	v_mul_f32_e32 v97, v85, v91
	v_fma_f32 v100, -v82, v96, v83
	v_div_scale_f32 v89, s[6:7], 2.0, v76, 2.0
	v_fmac_f32_e32 v93, v99, v93
	v_mul_f32_e32 v98, v87, v92
	v_fma_f32 v101, -v84, v97, v85
	v_fmac_f32_e32 v96, v100, v90
	v_mul_f32_e32 v99, v89, v93
	v_fma_f32 v102, -v86, v98, v87
	v_fmac_f32_e32 v97, v101, v91
	v_fma_f32 v82, -v82, v96, v83
	v_fma_f32 v103, -v88, v99, v89
	v_fmac_f32_e32 v98, v102, v92
	v_fma_f32 v83, -v84, v97, v85
	v_div_fmas_f32 v82, v82, v90, v96
	s_mov_b64 vcc, s[2:3]
	v_fmac_f32_e32 v99, v103, v93
	v_fma_f32 v84, -v86, v98, v87
	v_div_fixup_f32 v75, v82, v75, 2.0
	v_div_fmas_f32 v82, v83, v91, v97
	s_mov_b64 vcc, s[4:5]
	v_fma_f32 v85, -v88, v99, v89
	v_div_fixup_f32 v74, v82, v74, 2.0
	v_div_fmas_f32 v82, v84, v92, v98
	s_mov_b64 vcc, s[6:7]
	v_div_fixup_f32 v77, v82, v77, 2.0
	v_div_fmas_f32 v82, v85, v93, v99
	v_div_fixup_f32 v76, v82, v76, 2.0
	v_pk_add_f32 v[74:75], v[74:75], 1.0 op_sel_hi:[1,0] neg_lo:[1,0] neg_hi:[1,0]
	v_pk_add_f32 v[76:77], v[76:77], 1.0 op_sel_hi:[1,0] neg_lo:[1,0] neg_hi:[1,0]
	v_pk_add_f32 v[74:75], v[74:75], 1.0 op_sel_hi:[1,0]
	v_pk_add_f32 v[76:77], v[76:77], 1.0 op_sel_hi:[1,0]
	v_pk_mul_f32 v[74:75], v[78:79], v[74:75]
	v_pk_mul_f32 v[76:77], v[80:81], v[76:77]
	v_cvt_pk_bf16_f32 v74, v74, v75
	v_cvt_pk_bf16_f32 v75, v76, v77
	global_store_dwordx2 v[94:95], v[74:75], off
	s_waitcnt vmcnt(8)
	v_pk_add_f32 v[106:107], v[106:107], v[110:111]
	s_waitcnt vmcnt(7)
	v_pk_add_f32 v[106:107], v[106:107], v[114:115]
	v_pk_add_f32 v[108:109], v[108:109], v[112:113]
	s_waitcnt vmcnt(6)
	v_pk_add_f32 v[106:107], v[106:107], v[118:119]
	v_pk_add_f32 v[108:109], v[108:109], v[116:117]
	s_waitcnt lgkmcnt(0)
; DI uint2 pk4(float a, float b, float c, float d) { uint2 o; o.x = pk2(a, b); o.y = pk2(c, d); return o; }
; DI void phaseD1(int wv0, PP p, unsigned char* smem) {
;     ...
;     const int kv = e >> 18, rc = e & 262143, c4 = (rc & 63) * 4;
;     const size_t o = (size_t)kv * 4096 * 256 + (size_t)rc * 4;
;     float4 a = *(const float4*)(PART + o);
; #pragma unroll
;     for (int ks = 1; ks < 4; ++ks) {
;       const float4 t = *(const float4*)(PART + (size_t)ks * 2 * 4096 * 256 + o);
;       a.x += t.x; a.y += t.y; a.z += t.z; a.w += t.w;
;     }
;     const float* bv = sB + kv * 256 + c4;
;     *(uint2*)(HC + o) = pk4(gelu_t(a.x + bv[0]), gelu_t(a.y + bv[1]), gelu_t(a.z + bv[2]), gelu_t(a.w + bv[3]));
	v_pk_add_f32 v[106:107], v[106:107], v[122:123]
	v_pk_add_f32 v[108:109], v[108:109], v[120:121]
	v_mul_f32_e32 v114, 0x3d372713, v106
	v_mul_f32_e32 v115, 0x3d372713, v107
	v_pk_add_f32 v[108:109], v[108:109], v[124:125]
	v_mul_f32_e32 v114, v106, v114
	v_mul_f32_e32 v115, v107, v115
	v_pk_mul_f32 v[110:111], v[106:107], 0.5 op_sel_hi:[1,0]
	v_mul_f32_e32 v116, 0x3d372713, v108
	v_mul_f32_e32 v117, 0x3d372713, v109
	v_fma_f32 v106, v106, v114, v106
	v_fma_f32 v107, v107, v115, v107
	v_mul_f32_e32 v116, v108, v116
	v_mul_f32_e32 v117, v109, v117
	v_mul_f32_e32 v106, 0x3f4c422a, v106
	v_mul_f32_e32 v107, 0x3f4c422a, v107
	v_pk_mul_f32 v[112:113], v[108:109], 0.5 op_sel_hi:[1,0]
	v_fma_f32 v108, v108, v116, v108
	v_fma_f32 v109, v109, v117, v109
	v_add_f32_e32 v106, v106, v106
	v_add_f32_e32 v107, v107, v107
	v_mul_f32_e32 v108, 0x3f4c422a, v108
	v_mul_f32_e32 v109, 0x3f4c422a, v109
	v_mul_f32_e32 v106, 0x3fb8aa3b, v106
	v_mul_f32_e32 v107, 0x3fb8aa3b, v107
	v_add_f32_e32 v108, v108, v108
	v_add_f32_e32 v109, v109, v109
	v_exp_f32_e32 v106, v106
	v_exp_f32_e32 v107, v107
	v_mul_f32_e32 v108, 0x3fb8aa3b, v108
	v_mul_f32_e32 v109, 0x3fb8aa3b, v109
	v_exp_f32_e32 v108, v108
	v_exp_f32_e32 v109, v109
	v_pk_add_f32 v[106:107], v[106:107], 1.0 op_sel_hi:[1,0]
	v_pk_add_f32 v[108:109], v[108:109], 1.0 op_sel_hi:[1,0]
	v_div_scale_f32 v114, s[2:3], v107, v107, 2.0
	v_div_scale_f32 v116, s[2:3], v106, v106, 2.0
	v_rcp_f32_e32 v122, v114
	v_div_scale_f32 v118, s[4:5], v109, v109, 2.0
	v_rcp_f32_e32 v123, v116
	v_div_scale_f32 v120, s[6:7], v108, v108, 2.0
	v_rcp_f32_e32 v124, v118
	v_rcp_f32_e32 v125, v120
	v_fma_f32 v128, -v114, v122, 1.0
	v_div_scale_f32 v115, vcc, 2.0, v107, 2.0
	v_fma_f32 v129, -v116, v123, 1.0
	v_fmac_f32_e32 v122, v128, v122
	v_div_scale_f32 v117, s[2:3], 2.0, v106, 2.0
	v_fma_f32 v130, -v118, v124, 1.0
	v_fmac_f32_e32 v123, v129, v123
	v_mul_f32_e32 v128, v115, v122
	v_div_scale_f32 v119, s[4:5], 2.0, v109, 2.0
	v_fma_f32 v131, -v120, v125, 1.0
	v_fmac_f32_e32 v124, v130, v124
	v_mul_f32_e32 v129, v117, v123
	v_fma_f32 v132, -v114, v128, v115
	v_div_scale_f32 v121, s[6:7], 2.0, v108, 2.0
	v_fmac_f32_e32 v125, v131, v125
	v_mul_f32_e32 v130, v119, v124
	v_fma_f32 v133, -v116, v129, v117
	v_fmac_f32_e32 v128, v132, v122
	v_mul_f32_e32 v131, v121, v125
	v_fma_f32 v134, -v118, v130, v119
	v_fmac_f32_e32 v129, v133, v123
	v_fma_f32 v114, -v114, v128, v115
	v_fma_f32 v135, -v120, v131, v121
	v_fmac_f32_e32 v130, v134, v124
	v_fma_f32 v115, -v116, v129, v117
	v_div_fmas_f32 v114, v114, v122, v128
	s_mov_b64 vcc, s[2:3]
	v_fmac_f32_e32 v131, v135, v125
	v_fma_f32 v116, -v118, v130, v119
	v_div_fixup_f32 v107, v114, v107, 2.0
	v_div_fmas_f32 v114, v115, v123, v129
	s_mov_b64 vcc, s[4:5]
	v_fma_f32 v117, -v120, v131, v121
	v_div_fixup_f32 v106, v114, v106, 2.0
	v_div_fmas_f32 v114, v116, v124, v130
	s_mov_b64 vcc, s[6:7]
	v_div_fixup_f32 v109, v114, v109, 2.0
	v_div_fmas_f32 v114, v117, v125, v131
	v_div_fixup_f32 v108, v114, v108, 2.0
	v_pk_add_f32 v[106:107], v[106:107], 1.0 op_sel_hi:[1,0] neg_lo:[1,0] neg_hi:[1,0]
	v_pk_add_f32 v[108:109], v[108:109], 1.0 op_sel_hi:[1,0] neg_lo:[1,0] neg_hi:[1,0]
	v_pk_add_f32 v[106:107], v[106:107], 1.0 op_sel_hi:[1,0]
	v_pk_add_f32 v[108:109], v[108:109], 1.0 op_sel_hi:[1,0]
	v_pk_mul_f32 v[106:107], v[110:111], v[106:107]
	v_pk_mul_f32 v[108:109], v[112:113], v[108:109]
	v_cvt_pk_bf16_f32 v106, v106, v107
	v_cvt_pk_bf16_f32 v107, v108, v109
	global_store_dwordx2 v[126:127], v[106:107], off
	s_waitcnt vmcnt(5)
	v_pk_add_f32 v[152:153], v[152:153], v[156:157]
	s_waitcnt vmcnt(4)
	v_pk_add_f32 v[152:153], v[152:153], v[160:161]
	v_pk_add_f32 v[154:155], v[154:155], v[158:159]
	s_waitcnt vmcnt(3)
; DI uint2 pk4(float a, float b, float c, float d) { uint2 o; o.x = pk2(a, b); o.y = pk2(c, d); return o; }
; DI void phaseD1(int wv0, PP p, unsigned char* smem) {
;     ...
;     const int kv = e >> 18, rc = e & 262143, c4 = (rc & 63) * 4;
;     const size_t o = (size_t)kv * 4096 * 256 + (size_t)rc * 4;
;     float4 a = *(const float4*)(PART + o);
; #pragma unroll
;     for (int ks = 1; ks < 4; ++ks) {
;       const float4 t = *(const float4*)(PART + (size_t)ks * 2 * 4096 * 256 + o);
;       a.x += t.x; a.y += t.y; a.z += t.z; a.w += t.w;
;     }
;     const float* bv = sB + kv * 256 + c4;
;     *(uint2*)(HC + o) = pk4(gelu_t(a.x + bv[0]), gelu_t(a.y + bv[1]), gelu_t(a.z + bv[2]), gelu_t(a.w + bv[3]));
	v_pk_add_f32 v[152:153], v[152:153], v[164:165]
	v_pk_add_f32 v[154:155], v[154:155], v[162:163]
	s_waitcnt lgkmcnt(0)
	v_pk_add_f32 v[152:153], v[152:153], v[168:169]
	v_pk_add_f32 v[154:155], v[154:155], v[166:167]
	v_mul_f32_e32 v160, 0x3d372713, v152
	v_mul_f32_e32 v161, 0x3d372713, v153
	v_pk_add_f32 v[154:155], v[154:155], v[170:171]
	v_mul_f32_e32 v160, v152, v160
	v_mul_f32_e32 v161, v153, v161
	v_pk_mul_f32 v[156:157], v[152:153], 0.5 op_sel_hi:[1,0]
	v_mul_f32_e32 v162, 0x3d372713, v154
	v_mul_f32_e32 v163, 0x3d372713, v155
	v_fma_f32 v152, v152, v160, v152
	v_fma_f32 v153, v153, v161, v153
	v_mul_f32_e32 v162, v154, v162
	v_mul_f32_e32 v163, v155, v163
	v_mul_f32_e32 v152, 0x3f4c422a, v152
	v_mul_f32_e32 v153, 0x3f4c422a, v153
	v_pk_mul_f32 v[158:159], v[154:155], 0.5 op_sel_hi:[1,0]
	v_fma_f32 v154, v154, v162, v154
	v_fma_f32 v155, v155, v163, v155
	v_add_f32_e32 v152, v152, v152
	v_add_f32_e32 v153, v153, v153
	v_mul_f32_e32 v154, 0x3f4c422a, v154
	v_mul_f32_e32 v155, 0x3f4c422a, v155
	v_mul_f32_e32 v152, 0x3fb8aa3b, v152
	v_mul_f32_e32 v153, 0x3fb8aa3b, v153
	v_add_f32_e32 v154, v154, v154
	v_add_f32_e32 v155, v155, v155
	v_exp_f32_e32 v152, v152
	v_exp_f32_e32 v153, v153
	v_mul_f32_e32 v154, 0x3fb8aa3b, v154
	v_mul_f32_e32 v155, 0x3fb8aa3b, v155
	v_exp_f32_e32 v154, v154
	v_exp_f32_e32 v155, v155
	v_pk_add_f32 v[152:153], v[152:153], 1.0 op_sel_hi:[1,0]
	v_pk_add_f32 v[154:155], v[154:155], 1.0 op_sel_hi:[1,0]
	v_div_scale_f32 v160, s[2:3], v153, v153, 2.0
	v_div_scale_f32 v162, s[2:3], v152, v152, 2.0
	v_rcp_f32_e32 v168, v160
	v_div_scale_f32 v164, s[4:5], v155, v155, 2.0
	v_rcp_f32_e32 v169, v162
	v_div_scale_f32 v166, s[6:7], v154, v154, 2.0
	v_rcp_f32_e32 v170, v164
	v_rcp_f32_e32 v171, v166
	v_fma_f32 v174, -v160, v168, 1.0
	v_div_scale_f32 v161, vcc, 2.0, v153, 2.0
	v_fma_f32 v175, -v162, v169, 1.0
	v_fmac_f32_e32 v168, v174, v168
	v_div_scale_f32 v163, s[2:3], 2.0, v152, 2.0
	v_fma_f32 v176, -v164, v170, 1.0
	v_fmac_f32_e32 v169, v175, v169
	v_mul_f32_e32 v174, v161, v168
	v_div_scale_f32 v165, s[4:5], 2.0, v155, 2.0
	v_fma_f32 v177, -v166, v171, 1.0
	v_fmac_f32_e32 v170, v176, v170
	v_mul_f32_e32 v175, v163, v169
	v_fma_f32 v178, -v160, v174, v161
	v_div_scale_f32 v167, s[6:7], 2.0, v154, 2.0
	v_fmac_f32_e32 v171, v177, v171
	v_mul_f32_e32 v176, v165, v170
	v_fma_f32 v179, -v162, v175, v163
	v_fmac_f32_e32 v174, v178, v168
	v_mul_f32_e32 v177, v167, v171
	v_fma_f32 v180, -v164, v176, v165
	v_fmac_f32_e32 v175, v179, v169
	v_fma_f32 v160, -v160, v174, v161
	v_fma_f32 v181, -v166, v177, v167
	v_fmac_f32_e32 v176, v180, v170
	v_fma_f32 v161, -v162, v175, v163
	v_div_fmas_f32 v160, v160, v168, v174
	s_mov_b64 vcc, s[2:3]
	v_fmac_f32_e32 v177, v181, v171
	v_fma_f32 v162, -v164, v176, v165
	v_div_fixup_f32 v153, v160, v153, 2.0
	v_div_fmas_f32 v160, v161, v169, v175
	s_mov_b64 vcc, s[4:5]
	v_fma_f32 v163, -v166, v177, v167
	v_div_fixup_f32 v152, v160, v152, 2.0
	v_div_fmas_f32 v160, v162, v170, v176
	s_mov_b64 vcc, s[6:7]
	v_div_fixup_f32 v155, v160, v155, 2.0
	v_div_fmas_f32 v160, v163, v171, v177
	v_div_fixup_f32 v154, v160, v154, 2.0
	v_pk_add_f32 v[152:153], v[152:153], 1.0 op_sel_hi:[1,0] neg_lo:[1,0] neg_hi:[1,0]
	v_pk_add_f32 v[154:155], v[154:155], 1.0 op_sel_hi:[1,0] neg_lo:[1,0] neg_hi:[1,0]
	v_pk_add_f32 v[152:153], v[152:153], 1.0 op_sel_hi:[1,0]
	v_pk_add_f32 v[154:155], v[154:155], 1.0 op_sel_hi:[1,0]
	v_pk_mul_f32 v[152:153], v[156:157], v[152:153]
	v_pk_mul_f32 v[154:155], v[158:159], v[154:155]
	v_cvt_pk_bf16_f32 v152, v152, v153
	v_cvt_pk_bf16_f32 v153, v154, v155
	global_store_dwordx2 v[172:173], v[152:153], off
	s_branch .LBB0_524
